# SwiGLU epilogue: store addresses of row groups 2-8 by 64-bit increment from the previous group (SGPR constants) instead of v_or/v_add + v_mad_i64_i32 + v_lshl_add_u64 each (14 fewer VALU, 7 fewer 64-b
# baseline (speedup 1.0000x reference)
.LBB0_187:
	s_mov_b64 s[98:99], 0x16000
	s_mov_b64 s[100:101], 0x6e000
	v_mul_f32_e32 v151, 0xbfb8aa3b, v124
	v_exp_f32_e32 v151, v151
	v_mul_f32_e32 v154, 0xbfb8aa3b, v125
	v_exp_f32_e32 v154, v154
	v_lshl_or_b32 v142, s65, 7, v146
	v_add_f32_e32 v151, 1.0, v151
	v_rcp_f32_e32 v151, v151
	v_lshl_add_u32 v150, s36, 8, v144
	v_ashrrev_i32_e32 v143, 31, v142
	v_mov_b64_e32 v[140:141], s[22:23]
	v_mul_f32_e32 v124, v124, v151
	v_mul_f32_e32 v120, v120, v124
	v_add_f32_e32 v124, 1.0, v154
	v_mul_f32_e32 v151, 0xbfb8aa3b, v126
	v_rcp_f32_e32 v124, v124
	v_exp_f32_e32 v151, v151
	v_mul_f32_e32 v154, 0xbfb8aa3b, v127
	v_exp_f32_e32 v154, v154
	v_mul_f32_e32 v124, v125, v124
	v_add_f32_e32 v125, 1.0, v151
	v_rcp_f32_e32 v125, v125
	v_add_f32_e32 v151, 1.0, v154
	v_rcp_f32_e32 v151, v151
	v_mul_f32_e32 v121, v121, v124
	v_mul_f32_e32 v124, v126, v125
	v_mul_f32_e32 v125, 0xbfb8aa3b, v116
	v_exp_f32_e32 v125, v125
	v_mul_f32_e32 v122, v122, v124
	v_mul_f32_e32 v124, v127, v151
	v_mul_f32_e32 v123, v123, v124
	v_cvt_pk_bf16_f32 v120, v120, v121
	v_cvt_pk_bf16_f32 v121, v122, v123
	v_add_f32_e32 v122, 1.0, v125
	v_rcp_f32_e32 v122, v122
	v_mul_f32_e32 v123, 0xbfb8aa3b, v117
	v_exp_f32_e32 v123, v123
	v_mad_i64_i32 v[152:153], s[44:45], v150, s64, v[140:141]
	v_lshlrev_b64 v[142:143], 1, v[142:143]
	v_lshl_add_u64 v[152:153], v[152:153], 0, v[142:143]
	v_mul_f32_e32 v116, v116, v122
	global_store_dwordx2 v[152:153], v[120:121], off
	v_mul_f32_e32 v112, v112, v116
	v_add_f32_e32 v116, 1.0, v123
	v_mul_f32_e32 v120, 0xbfb8aa3b, v118
	v_rcp_f32_e32 v116, v116
	v_exp_f32_e32 v120, v120
	v_mul_f32_e32 v121, 0xbfb8aa3b, v119
	v_exp_f32_e32 v121, v121
	v_mul_f32_e32 v116, v117, v116
	v_add_f32_e32 v117, 1.0, v120
	v_rcp_f32_e32 v117, v117
	v_add_f32_e32 v120, 1.0, v121
	v_rcp_f32_e32 v120, v120
	v_mul_f32_e32 v113, v113, v116
	v_mul_f32_e32 v116, v118, v117
	v_mul_f32_e32 v114, v114, v116
	v_mul_f32_e32 v116, v119, v120
	v_cvt_pk_bf16_f32 v112, v112, v113
	v_mul_f32_e32 v115, v115, v116
	v_cvt_pk_bf16_f32 v113, v114, v115
	global_store_dwordx2 v[152:153], v[112:113], off offset:128
	v_mul_f32_e32 v112, 0xbfb8aa3b, v108
	v_exp_f32_e32 v114, v112
	v_mul_f32_e32 v115, 0xbfb8aa3b, v109
	v_exp_f32_e32 v115, v115
	v_add_f32_e32 v114, 1.0, v114
	v_rcp_f32_e32 v114, v114
	v_lshl_add_u64 v[112:113], v[152:153], 0, s[98:99]
	v_mul_f32_e32 v108, v108, v114
	v_mul_f32_e32 v104, v104, v108
	v_add_f32_e32 v108, 1.0, v115
	v_mul_f32_e32 v114, 0xbfb8aa3b, v110
	v_rcp_f32_e32 v108, v108
	v_exp_f32_e32 v114, v114
	v_mul_f32_e32 v115, 0xbfb8aa3b, v111
	v_exp_f32_e32 v115, v115
	v_mul_f32_e32 v108, v109, v108
	v_add_f32_e32 v109, 1.0, v114
	v_rcp_f32_e32 v109, v109
	v_add_f32_e32 v114, 1.0, v115
	v_rcp_f32_e32 v114, v114
	v_mul_f32_e32 v105, v105, v108
	v_mul_f32_e32 v108, v110, v109
	v_mul_f32_e32 v109, 0xbfb8aa3b, v100
	v_exp_f32_e32 v109, v109
	v_mul_f32_e32 v106, v106, v108
	v_mul_f32_e32 v108, v111, v114
	v_mul_f32_e32 v107, v107, v108
	v_cvt_pk_bf16_f32 v104, v104, v105
	v_cvt_pk_bf16_f32 v105, v106, v107
	v_add_f32_e32 v106, 1.0, v109
	v_rcp_f32_e32 v106, v106
	v_mul_f32_e32 v107, 0xbfb8aa3b, v101
	v_exp_f32_e32 v107, v107
	global_store_dwordx2 v[112:113], v[104:105], off
	v_mul_f32_e32 v100, v100, v106
	v_mul_f32_e32 v96, v96, v100
	v_add_f32_e32 v100, 1.0, v107
	v_mul_f32_e32 v104, 0xbfb8aa3b, v102
	v_rcp_f32_e32 v100, v100
	v_exp_f32_e32 v104, v104
	v_mul_f32_e32 v105, 0xbfb8aa3b, v103
	v_exp_f32_e32 v105, v105
	v_mul_f32_e32 v100, v101, v100
	v_add_f32_e32 v101, 1.0, v104
	v_rcp_f32_e32 v101, v101
	v_add_f32_e32 v104, 1.0, v105
	v_rcp_f32_e32 v104, v104
	v_mul_f32_e32 v97, v97, v100
	v_mul_f32_e32 v100, v102, v101
	v_mul_f32_e32 v98, v98, v100
	v_mul_f32_e32 v100, v103, v104
	v_cvt_pk_bf16_f32 v96, v96, v97
	v_mul_f32_e32 v99, v99, v100
	v_cvt_pk_bf16_f32 v97, v98, v99
	global_store_dwordx2 v[112:113], v[96:97], off offset:128
	v_mul_f32_e32 v96, 0xbfb8aa3b, v92
	v_exp_f32_e32 v98, v96
	v_mul_f32_e32 v99, 0xbfb8aa3b, v93
	v_exp_f32_e32 v99, v99
	v_add_f32_e32 v98, 1.0, v98
	v_rcp_f32_e32 v98, v98
	v_lshl_add_u64 v[96:97], v[112:113], 0, s[98:99]
	v_mul_f32_e32 v92, v92, v98
	v_mul_f32_e32 v88, v88, v92
	v_add_f32_e32 v92, 1.0, v99
	v_mul_f32_e32 v98, 0xbfb8aa3b, v94
	v_rcp_f32_e32 v92, v92
	v_exp_f32_e32 v98, v98
	v_mul_f32_e32 v99, 0xbfb8aa3b, v95
	v_exp_f32_e32 v99, v99
	v_mul_f32_e32 v92, v93, v92
	v_add_f32_e32 v93, 1.0, v98
	v_rcp_f32_e32 v93, v93
	v_add_f32_e32 v98, 1.0, v99
	v_rcp_f32_e32 v98, v98
	v_mul_f32_e32 v89, v89, v92
	v_mul_f32_e32 v92, v94, v93
	v_mul_f32_e32 v93, 0xbfb8aa3b, v84
	v_exp_f32_e32 v93, v93
	v_mul_f32_e32 v90, v90, v92
	v_mul_f32_e32 v92, v95, v98
	v_mul_f32_e32 v91, v91, v92
	v_cvt_pk_bf16_f32 v88, v88, v89
	v_cvt_pk_bf16_f32 v89, v90, v91
	v_add_f32_e32 v90, 1.0, v93
	v_rcp_f32_e32 v90, v90
	v_mul_f32_e32 v91, 0xbfb8aa3b, v85
	v_exp_f32_e32 v91, v91
	global_store_dwordx2 v[96:97], v[88:89], off
	v_mul_f32_e32 v84, v84, v90
	v_mul_f32_e32 v80, v80, v84
	v_add_f32_e32 v84, 1.0, v91
	v_mul_f32_e32 v88, 0xbfb8aa3b, v86
	v_rcp_f32_e32 v84, v84
	v_exp_f32_e32 v88, v88
	v_mul_f32_e32 v89, 0xbfb8aa3b, v87
	v_exp_f32_e32 v89, v89
	v_mul_f32_e32 v84, v85, v84
	v_add_f32_e32 v85, 1.0, v88
	v_rcp_f32_e32 v85, v85
	v_add_f32_e32 v88, 1.0, v89
	v_rcp_f32_e32 v88, v88
	v_mul_f32_e32 v81, v81, v84
	v_mul_f32_e32 v84, v86, v85
	v_mul_f32_e32 v82, v82, v84
	v_mul_f32_e32 v84, v87, v88
	v_cvt_pk_bf16_f32 v80, v80, v81
	v_mul_f32_e32 v83, v83, v84
	v_cvt_pk_bf16_f32 v81, v82, v83
	global_store_dwordx2 v[96:97], v[80:81], off offset:128
	v_mul_f32_e32 v80, 0xbfb8aa3b, v76
	v_exp_f32_e32 v82, v80
	v_mul_f32_e32 v83, 0xbfb8aa3b, v77
	v_exp_f32_e32 v83, v83
	v_add_f32_e32 v82, 1.0, v82
	v_rcp_f32_e32 v82, v82
	v_lshl_add_u64 v[80:81], v[96:97], 0, s[98:99]
	v_mul_f32_e32 v76, v76, v82
	v_mul_f32_e32 v72, v72, v76
	v_add_f32_e32 v76, 1.0, v83
	v_mul_f32_e32 v82, 0xbfb8aa3b, v78
	v_rcp_f32_e32 v76, v76
	v_exp_f32_e32 v82, v82
	v_mul_f32_e32 v83, 0xbfb8aa3b, v79
	v_exp_f32_e32 v83, v83
	v_mul_f32_e32 v76, v77, v76
	v_add_f32_e32 v77, 1.0, v82
	v_rcp_f32_e32 v77, v77
	v_add_f32_e32 v82, 1.0, v83
	v_rcp_f32_e32 v82, v82
	v_mul_f32_e32 v73, v73, v76
	v_mul_f32_e32 v76, v78, v77
	v_mul_f32_e32 v77, 0xbfb8aa3b, v68
	v_exp_f32_e32 v77, v77
	v_mul_f32_e32 v74, v74, v76
	v_mul_f32_e32 v76, v79, v82
	v_mul_f32_e32 v75, v75, v76
	v_cvt_pk_bf16_f32 v72, v72, v73
	v_cvt_pk_bf16_f32 v73, v74, v75
	v_add_f32_e32 v74, 1.0, v77
	v_rcp_f32_e32 v74, v74
	v_mul_f32_e32 v75, 0xbfb8aa3b, v69
	v_exp_f32_e32 v75, v75
	global_store_dwordx2 v[80:81], v[72:73], off
	v_mul_f32_e32 v68, v68, v74
	v_mul_f32_e32 v64, v64, v68
	v_add_f32_e32 v68, 1.0, v75
	v_mul_f32_e32 v72, 0xbfb8aa3b, v70
	v_rcp_f32_e32 v68, v68
	v_exp_f32_e32 v72, v72
	v_mul_f32_e32 v73, 0xbfb8aa3b, v71
	v_exp_f32_e32 v73, v73
	v_mul_f32_e32 v68, v69, v68
	v_add_f32_e32 v69, 1.0, v72
	v_rcp_f32_e32 v69, v69
	v_add_f32_e32 v72, 1.0, v73
	v_rcp_f32_e32 v72, v72
	v_mul_f32_e32 v65, v65, v68
	v_mul_f32_e32 v68, v70, v69
	v_mul_f32_e32 v66, v66, v68
	v_mul_f32_e32 v68, v71, v72
	v_cvt_pk_bf16_f32 v64, v64, v65
	v_mul_f32_e32 v67, v67, v68
	v_cvt_pk_bf16_f32 v65, v66, v67
	global_store_dwordx2 v[80:81], v[64:65], off offset:128
	v_mul_f32_e32 v64, 0xbfb8aa3b, v60
	v_exp_f32_e32 v66, v64
	v_mul_f32_e32 v67, 0xbfb8aa3b, v61
	v_exp_f32_e32 v67, v67
	v_add_f32_e32 v66, 1.0, v66
	v_rcp_f32_e32 v66, v66
	v_lshl_add_u64 v[64:65], v[80:81], 0, s[100:101]
	v_mul_f32_e32 v60, v60, v66
	v_mul_f32_e32 v56, v56, v60
	v_add_f32_e32 v60, 1.0, v67
	v_mul_f32_e32 v66, 0xbfb8aa3b, v62
	v_rcp_f32_e32 v60, v60
	v_exp_f32_e32 v66, v66
	v_mul_f32_e32 v67, 0xbfb8aa3b, v63
	v_exp_f32_e32 v67, v67
	v_mul_f32_e32 v60, v61, v60
	v_add_f32_e32 v61, 1.0, v66
	v_rcp_f32_e32 v61, v61
	v_add_f32_e32 v66, 1.0, v67
	v_rcp_f32_e32 v66, v66
	v_mul_f32_e32 v57, v57, v60
	v_mul_f32_e32 v60, v62, v61
	v_mul_f32_e32 v61, 0xbfb8aa3b, v52
	v_exp_f32_e32 v61, v61
	v_mul_f32_e32 v58, v58, v60
	v_mul_f32_e32 v60, v63, v66
	v_mul_f32_e32 v59, v59, v60
	v_cvt_pk_bf16_f32 v56, v56, v57
	v_cvt_pk_bf16_f32 v57, v58, v59
	v_add_f32_e32 v58, 1.0, v61
	v_rcp_f32_e32 v58, v58
	v_mul_f32_e32 v59, 0xbfb8aa3b, v53
	v_exp_f32_e32 v59, v59
	global_store_dwordx2 v[64:65], v[56:57], off
	v_mul_f32_e32 v52, v52, v58
	v_mul_f32_e32 v48, v48, v52
	v_add_f32_e32 v52, 1.0, v59
	v_mul_f32_e32 v56, 0xbfb8aa3b, v54
	v_rcp_f32_e32 v52, v52
	v_exp_f32_e32 v56, v56
	v_mul_f32_e32 v57, 0xbfb8aa3b, v55
	v_exp_f32_e32 v57, v57
	v_mul_f32_e32 v52, v53, v52
	v_add_f32_e32 v53, 1.0, v56
	v_rcp_f32_e32 v53, v53
	v_add_f32_e32 v56, 1.0, v57
	v_rcp_f32_e32 v56, v56
	v_mul_f32_e32 v49, v49, v52
	v_mul_f32_e32 v52, v54, v53
	v_mul_f32_e32 v50, v50, v52
	v_mul_f32_e32 v52, v55, v56
	v_cvt_pk_bf16_f32 v48, v48, v49
	v_mul_f32_e32 v51, v51, v52
	v_cvt_pk_bf16_f32 v49, v50, v51
	global_store_dwordx2 v[64:65], v[48:49], off offset:128
	v_mul_f32_e32 v48, 0xbfb8aa3b, v44
	v_exp_f32_e32 v50, v48
	v_mul_f32_e32 v51, 0xbfb8aa3b, v45
	v_exp_f32_e32 v51, v51
	v_add_f32_e32 v50, 1.0, v50
	v_rcp_f32_e32 v50, v50
	v_lshl_add_u64 v[48:49], v[64:65], 0, s[98:99]
	v_mul_f32_e32 v44, v44, v50
	v_mul_f32_e32 v40, v40, v44
	v_add_f32_e32 v44, 1.0, v51
	v_mul_f32_e32 v50, 0xbfb8aa3b, v46
	v_rcp_f32_e32 v44, v44
	v_exp_f32_e32 v50, v50
	v_mul_f32_e32 v51, 0xbfb8aa3b, v47
	v_exp_f32_e32 v51, v51
	v_mul_f32_e32 v44, v45, v44
	v_add_f32_e32 v45, 1.0, v50
	v_rcp_f32_e32 v45, v45
	v_add_f32_e32 v50, 1.0, v51
	v_rcp_f32_e32 v50, v50
	v_mul_f32_e32 v41, v41, v44
	v_mul_f32_e32 v44, v46, v45
	v_mul_f32_e32 v45, 0xbfb8aa3b, v36
	v_exp_f32_e32 v45, v45
	v_mul_f32_e32 v42, v42, v44
	v_mul_f32_e32 v44, v47, v50
	v_mul_f32_e32 v43, v43, v44
	v_cvt_pk_bf16_f32 v40, v40, v41
	v_cvt_pk_bf16_f32 v41, v42, v43
	v_add_f32_e32 v42, 1.0, v45
	v_rcp_f32_e32 v42, v42
	v_mul_f32_e32 v43, 0xbfb8aa3b, v37
	v_exp_f32_e32 v43, v43
	global_store_dwordx2 v[48:49], v[40:41], off
	v_mul_f32_e32 v36, v36, v42
	v_mul_f32_e32 v32, v32, v36
	v_add_f32_e32 v36, 1.0, v43
	v_mul_f32_e32 v40, 0xbfb8aa3b, v38
	v_rcp_f32_e32 v36, v36
	v_exp_f32_e32 v40, v40
	v_mul_f32_e32 v41, 0xbfb8aa3b, v39
	v_exp_f32_e32 v41, v41
	v_mul_f32_e32 v36, v37, v36
	v_add_f32_e32 v37, 1.0, v40
	v_rcp_f32_e32 v37, v37
	v_add_f32_e32 v40, 1.0, v41
	v_rcp_f32_e32 v40, v40
	v_mul_f32_e32 v33, v33, v36
	v_mul_f32_e32 v36, v38, v37
	v_mul_f32_e32 v34, v34, v36
	v_mul_f32_e32 v36, v39, v40
	v_cvt_pk_bf16_f32 v32, v32, v33
	v_mul_f32_e32 v35, v35, v36
	v_cvt_pk_bf16_f32 v33, v34, v35
	global_store_dwordx2 v[48:49], v[32:33], off offset:128
	v_mul_f32_e32 v32, 0xbfb8aa3b, v28
	v_exp_f32_e32 v34, v32
	v_mul_f32_e32 v35, 0xbfb8aa3b, v29
	v_exp_f32_e32 v35, v35
	v_add_f32_e32 v34, 1.0, v34
	v_rcp_f32_e32 v34, v34
	v_lshl_add_u64 v[32:33], v[48:49], 0, s[98:99]
	v_mul_f32_e32 v28, v28, v34
	v_mul_f32_e32 v24, v24, v28
	v_add_f32_e32 v28, 1.0, v35
	v_mul_f32_e32 v34, 0xbfb8aa3b, v30
	v_rcp_f32_e32 v28, v28
	v_exp_f32_e32 v34, v34
	v_mul_f32_e32 v35, 0xbfb8aa3b, v31
	v_exp_f32_e32 v35, v35
	v_mul_f32_e32 v28, v29, v28
	v_add_f32_e32 v29, 1.0, v34
	v_rcp_f32_e32 v29, v29
	v_add_f32_e32 v34, 1.0, v35
	v_rcp_f32_e32 v34, v34
	v_mul_f32_e32 v25, v25, v28
	v_mul_f32_e32 v28, v30, v29
	v_mul_f32_e32 v29, 0xbfb8aa3b, v20
	v_exp_f32_e32 v29, v29
	v_mul_f32_e32 v26, v26, v28
	v_mul_f32_e32 v28, v31, v34
	v_mul_f32_e32 v27, v27, v28
	v_cvt_pk_bf16_f32 v24, v24, v25
	v_cvt_pk_bf16_f32 v25, v26, v27
	v_add_f32_e32 v26, 1.0, v29
	v_rcp_f32_e32 v26, v26
	v_mul_f32_e32 v27, 0xbfb8aa3b, v21
	v_exp_f32_e32 v27, v27
	global_store_dwordx2 v[32:33], v[24:25], off
	v_mul_f32_e32 v20, v20, v26
	v_mul_f32_e32 v16, v16, v20
	v_add_f32_e32 v20, 1.0, v27
	v_mul_f32_e32 v24, 0xbfb8aa3b, v22
	v_rcp_f32_e32 v20, v20
	v_exp_f32_e32 v24, v24
	v_mul_f32_e32 v25, 0xbfb8aa3b, v23
	v_exp_f32_e32 v25, v25
	v_mul_f32_e32 v20, v21, v20
	v_add_f32_e32 v21, 1.0, v24
	v_rcp_f32_e32 v21, v21
	v_add_f32_e32 v24, 1.0, v25
	v_rcp_f32_e32 v24, v24
	v_mul_f32_e32 v17, v17, v20
	v_mul_f32_e32 v20, v22, v21
	v_mul_f32_e32 v18, v18, v20
	v_mul_f32_e32 v20, v23, v24
	v_cvt_pk_bf16_f32 v16, v16, v17
	v_mul_f32_e32 v19, v19, v20
	v_cvt_pk_bf16_f32 v17, v18, v19
	global_store_dwordx2 v[32:33], v[16:17], off offset:128
	v_mul_f32_e32 v16, 0xbfb8aa3b, v12
	v_exp_f32_e32 v18, v16
	v_mul_f32_e32 v19, 0xbfb8aa3b, v13
	v_exp_f32_e32 v19, v19
	v_add_f32_e32 v18, 1.0, v18
	v_rcp_f32_e32 v18, v18
	v_lshl_add_u64 v[16:17], v[32:33], 0, s[98:99]
	v_mul_f32_e32 v12, v12, v18
	v_mul_f32_e32 v8, v8, v12
	v_add_f32_e32 v12, 1.0, v19
	v_mul_f32_e32 v18, 0xbfb8aa3b, v14
	v_rcp_f32_e32 v12, v12
	v_exp_f32_e32 v18, v18
	v_mul_f32_e32 v19, 0xbfb8aa3b, v15
	v_exp_f32_e32 v19, v19
	v_mul_f32_e32 v12, v13, v12
	v_add_f32_e32 v13, 1.0, v18
	v_rcp_f32_e32 v13, v13
	v_add_f32_e32 v18, 1.0, v19
	v_rcp_f32_e32 v18, v18
	v_mul_f32_e32 v9, v9, v12
	v_mul_f32_e32 v12, v14, v13
	v_mul_f32_e32 v13, 0xbfb8aa3b, v4
	v_exp_f32_e32 v13, v13
	v_mul_f32_e32 v10, v10, v12
	v_mul_f32_e32 v12, v15, v18
	v_mul_f32_e32 v11, v11, v12
	v_cvt_pk_bf16_f32 v8, v8, v9
	v_cvt_pk_bf16_f32 v9, v10, v11
	v_add_f32_e32 v10, 1.0, v13
	v_rcp_f32_e32 v10, v10
	v_mul_f32_e32 v11, 0xbfb8aa3b, v5
	v_exp_f32_e32 v11, v11
	global_store_dwordx2 v[16:17], v[8:9], off
	v_mul_f32_e32 v4, v4, v10
	v_mul_f32_e32 v0, v0, v4
	v_add_f32_e32 v4, 1.0, v11
	v_mul_f32_e32 v8, 0xbfb8aa3b, v6
	v_rcp_f32_e32 v4, v4
	v_exp_f32_e32 v8, v8
	v_mul_f32_e32 v9, 0xbfb8aa3b, v7
	v_exp_f32_e32 v9, v9
	v_mul_f32_e32 v4, v5, v4
	v_add_f32_e32 v5, 1.0, v8
	v_rcp_f32_e32 v5, v5
	v_add_f32_e32 v8, 1.0, v9
	v_rcp_f32_e32 v8, v8
	v_mul_f32_e32 v1, v1, v4
	v_mul_f32_e32 v4, v6, v5
	v_mul_f32_e32 v2, v2, v4
	v_mul_f32_e32 v4, v7, v8
	s_andn2_b64 vcc, exec, s[4:5]
	s_mov_b64 s[4:5], -1
	v_mul_f32_e32 v3, v3, v4
	v_cvt_pk_bf16_f32 v0, v0, v1
	v_cvt_pk_bf16_f32 v1, v2, v3
	global_store_dwordx2 v[16:17], v[0:1], off offset:128
	s_cbranch_vccnz .LBB0_180
	s_andn2_b64 vcc, exec, s[0:1]
	s_cbranch_vccnz .LBB0_179
	s_barrier
	s_branch .LBB0_179

.LBB0_727:
	s_mov_b64 s[98:99], 0x16000
	s_mov_b64 s[100:101], 0x6e000
	v_mul_f32_e32 v151, 0xbfb8aa3b, v124
	v_exp_f32_e32 v151, v151
	v_mul_f32_e32 v154, 0xbfb8aa3b, v125
	v_exp_f32_e32 v154, v154
	v_lshl_or_b32 v142, s69, 7, v146
	v_add_f32_e32 v151, 1.0, v151
	v_rcp_f32_e32 v151, v151
	v_lshl_add_u32 v150, s46, 8, v144
	v_ashrrev_i32_e32 v143, 31, v142
	v_mov_b64_e32 v[140:141], s[22:23]
	v_mul_f32_e32 v124, v124, v151
	v_mul_f32_e32 v120, v120, v124
	v_add_f32_e32 v124, 1.0, v154
	v_mul_f32_e32 v151, 0xbfb8aa3b, v126
	v_rcp_f32_e32 v124, v124
	v_exp_f32_e32 v151, v151
	v_mul_f32_e32 v154, 0xbfb8aa3b, v127
	v_exp_f32_e32 v154, v154
	v_mul_f32_e32 v124, v125, v124
	v_add_f32_e32 v125, 1.0, v151
	v_rcp_f32_e32 v125, v125
	v_add_f32_e32 v151, 1.0, v154
	v_rcp_f32_e32 v151, v151
	v_mul_f32_e32 v121, v121, v124
	v_mul_f32_e32 v124, v126, v125
	v_mul_f32_e32 v125, 0xbfb8aa3b, v116
	v_exp_f32_e32 v125, v125
	v_mul_f32_e32 v122, v122, v124
	v_mul_f32_e32 v124, v127, v151
	v_mul_f32_e32 v123, v123, v124
	v_cvt_pk_bf16_f32 v120, v120, v121
	v_cvt_pk_bf16_f32 v121, v122, v123
	v_add_f32_e32 v122, 1.0, v125
	v_rcp_f32_e32 v122, v122
	v_mul_f32_e32 v123, 0xbfb8aa3b, v117
	v_exp_f32_e32 v123, v123
	v_mad_i64_i32 v[152:153], s[48:49], v150, s68, v[140:141]
	v_lshlrev_b64 v[142:143], 1, v[142:143]
	v_lshl_add_u64 v[152:153], v[152:153], 0, v[142:143]
	v_mul_f32_e32 v116, v116, v122
	global_store_dwordx2 v[152:153], v[120:121], off
	v_mul_f32_e32 v112, v112, v116
	v_add_f32_e32 v116, 1.0, v123
	v_mul_f32_e32 v120, 0xbfb8aa3b, v118
	v_rcp_f32_e32 v116, v116
	v_exp_f32_e32 v120, v120
	v_mul_f32_e32 v121, 0xbfb8aa3b, v119
	v_exp_f32_e32 v121, v121
	v_mul_f32_e32 v116, v117, v116
	v_add_f32_e32 v117, 1.0, v120
	v_rcp_f32_e32 v117, v117
	v_add_f32_e32 v120, 1.0, v121
	v_rcp_f32_e32 v120, v120
	v_mul_f32_e32 v113, v113, v116
	v_mul_f32_e32 v116, v118, v117
	v_mul_f32_e32 v114, v114, v116
	v_mul_f32_e32 v116, v119, v120
	v_cvt_pk_bf16_f32 v112, v112, v113
	v_mul_f32_e32 v115, v115, v116
	v_cvt_pk_bf16_f32 v113, v114, v115
	global_store_dwordx2 v[152:153], v[112:113], off offset:128
	v_mul_f32_e32 v112, 0xbfb8aa3b, v108
	v_exp_f32_e32 v114, v112
	v_mul_f32_e32 v115, 0xbfb8aa3b, v109
	v_exp_f32_e32 v115, v115
	v_add_f32_e32 v114, 1.0, v114
	v_rcp_f32_e32 v114, v114
	v_lshl_add_u64 v[112:113], v[152:153], 0, s[98:99]
	v_mul_f32_e32 v108, v108, v114
	v_mul_f32_e32 v104, v104, v108
	v_add_f32_e32 v108, 1.0, v115
	v_mul_f32_e32 v114, 0xbfb8aa3b, v110
	v_rcp_f32_e32 v108, v108
	v_exp_f32_e32 v114, v114
	v_mul_f32_e32 v115, 0xbfb8aa3b, v111
	v_exp_f32_e32 v115, v115
	v_mul_f32_e32 v108, v109, v108
	v_add_f32_e32 v109, 1.0, v114
	v_rcp_f32_e32 v109, v109
	v_add_f32_e32 v114, 1.0, v115
	v_rcp_f32_e32 v114, v114
	v_mul_f32_e32 v105, v105, v108
	v_mul_f32_e32 v108, v110, v109
	v_mul_f32_e32 v109, 0xbfb8aa3b, v100
	v_exp_f32_e32 v109, v109
	v_mul_f32_e32 v106, v106, v108
	v_mul_f32_e32 v108, v111, v114
	v_mul_f32_e32 v107, v107, v108
	v_cvt_pk_bf16_f32 v104, v104, v105
	v_cvt_pk_bf16_f32 v105, v106, v107
	v_add_f32_e32 v106, 1.0, v109
	v_rcp_f32_e32 v106, v106
	v_mul_f32_e32 v107, 0xbfb8aa3b, v101
	v_exp_f32_e32 v107, v107
	global_store_dwordx2 v[112:113], v[104:105], off
	v_mul_f32_e32 v100, v100, v106
	v_mul_f32_e32 v96, v96, v100
	v_add_f32_e32 v100, 1.0, v107
	v_mul_f32_e32 v104, 0xbfb8aa3b, v102
	v_rcp_f32_e32 v100, v100
	v_exp_f32_e32 v104, v104
	v_mul_f32_e32 v105, 0xbfb8aa3b, v103
	v_exp_f32_e32 v105, v105
	v_mul_f32_e32 v100, v101, v100
	v_add_f32_e32 v101, 1.0, v104
	v_rcp_f32_e32 v101, v101
	v_add_f32_e32 v104, 1.0, v105
	v_rcp_f32_e32 v104, v104
	v_mul_f32_e32 v97, v97, v100
	v_mul_f32_e32 v100, v102, v101
	v_mul_f32_e32 v98, v98, v100
	v_mul_f32_e32 v100, v103, v104
	v_cvt_pk_bf16_f32 v96, v96, v97
	v_mul_f32_e32 v99, v99, v100
	v_cvt_pk_bf16_f32 v97, v98, v99
	global_store_dwordx2 v[112:113], v[96:97], off offset:128
	v_mul_f32_e32 v96, 0xbfb8aa3b, v92
	v_exp_f32_e32 v98, v96
	v_mul_f32_e32 v99, 0xbfb8aa3b, v93
	v_exp_f32_e32 v99, v99
	v_add_f32_e32 v98, 1.0, v98
	v_rcp_f32_e32 v98, v98
	v_lshl_add_u64 v[96:97], v[112:113], 0, s[98:99]
	v_mul_f32_e32 v92, v92, v98
	v_mul_f32_e32 v88, v88, v92
	v_add_f32_e32 v92, 1.0, v99
	v_mul_f32_e32 v98, 0xbfb8aa3b, v94
	v_rcp_f32_e32 v92, v92
	v_exp_f32_e32 v98, v98
	v_mul_f32_e32 v99, 0xbfb8aa3b, v95
	v_exp_f32_e32 v99, v99
	v_mul_f32_e32 v92, v93, v92
	v_add_f32_e32 v93, 1.0, v98
	v_rcp_f32_e32 v93, v93
	v_add_f32_e32 v98, 1.0, v99
	v_rcp_f32_e32 v98, v98
	v_mul_f32_e32 v89, v89, v92
	v_mul_f32_e32 v92, v94, v93
	v_mul_f32_e32 v93, 0xbfb8aa3b, v84
	v_exp_f32_e32 v93, v93
	v_mul_f32_e32 v90, v90, v92
	v_mul_f32_e32 v92, v95, v98
	v_mul_f32_e32 v91, v91, v92
	v_cvt_pk_bf16_f32 v88, v88, v89
	v_cvt_pk_bf16_f32 v89, v90, v91
	v_add_f32_e32 v90, 1.0, v93
	v_rcp_f32_e32 v90, v90
	v_mul_f32_e32 v91, 0xbfb8aa3b, v85
	v_exp_f32_e32 v91, v91
	global_store_dwordx2 v[96:97], v[88:89], off
	v_mul_f32_e32 v84, v84, v90
	v_mul_f32_e32 v80, v80, v84
	v_add_f32_e32 v84, 1.0, v91
	v_mul_f32_e32 v88, 0xbfb8aa3b, v86
	v_rcp_f32_e32 v84, v84
	v_exp_f32_e32 v88, v88
	v_mul_f32_e32 v89, 0xbfb8aa3b, v87
	v_exp_f32_e32 v89, v89
	v_mul_f32_e32 v84, v85, v84
	v_add_f32_e32 v85, 1.0, v88
	v_rcp_f32_e32 v85, v85
	v_add_f32_e32 v88, 1.0, v89
	v_rcp_f32_e32 v88, v88
	v_mul_f32_e32 v81, v81, v84
	v_mul_f32_e32 v84, v86, v85
	v_mul_f32_e32 v82, v82, v84
	v_mul_f32_e32 v84, v87, v88
	v_cvt_pk_bf16_f32 v80, v80, v81
	v_mul_f32_e32 v83, v83, v84
	v_cvt_pk_bf16_f32 v81, v82, v83
	global_store_dwordx2 v[96:97], v[80:81], off offset:128
	v_mul_f32_e32 v80, 0xbfb8aa3b, v76
	v_exp_f32_e32 v82, v80
	v_mul_f32_e32 v83, 0xbfb8aa3b, v77
	v_exp_f32_e32 v83, v83
	v_add_f32_e32 v82, 1.0, v82
	v_rcp_f32_e32 v82, v82
	v_lshl_add_u64 v[80:81], v[96:97], 0, s[98:99]
	v_mul_f32_e32 v76, v76, v82
	v_mul_f32_e32 v72, v72, v76
	v_add_f32_e32 v76, 1.0, v83
	v_mul_f32_e32 v82, 0xbfb8aa3b, v78
	v_rcp_f32_e32 v76, v76
	v_exp_f32_e32 v82, v82
	v_mul_f32_e32 v83, 0xbfb8aa3b, v79
	v_exp_f32_e32 v83, v83
	v_mul_f32_e32 v76, v77, v76
	v_add_f32_e32 v77, 1.0, v82
	v_rcp_f32_e32 v77, v77
	v_add_f32_e32 v82, 1.0, v83
	v_rcp_f32_e32 v82, v82
	v_mul_f32_e32 v73, v73, v76
	v_mul_f32_e32 v76, v78, v77
	v_mul_f32_e32 v77, 0xbfb8aa3b, v68
	v_exp_f32_e32 v77, v77
	v_mul_f32_e32 v74, v74, v76
	v_mul_f32_e32 v76, v79, v82
	v_mul_f32_e32 v75, v75, v76
	v_cvt_pk_bf16_f32 v72, v72, v73
	v_cvt_pk_bf16_f32 v73, v74, v75
	v_add_f32_e32 v74, 1.0, v77
	v_rcp_f32_e32 v74, v74
	v_mul_f32_e32 v75, 0xbfb8aa3b, v69
	v_exp_f32_e32 v75, v75
	global_store_dwordx2 v[80:81], v[72:73], off
	v_mul_f32_e32 v68, v68, v74
	v_mul_f32_e32 v64, v64, v68
	v_add_f32_e32 v68, 1.0, v75
	v_mul_f32_e32 v72, 0xbfb8aa3b, v70
	v_rcp_f32_e32 v68, v68
	v_exp_f32_e32 v72, v72
	v_mul_f32_e32 v73, 0xbfb8aa3b, v71
	v_exp_f32_e32 v73, v73
	v_mul_f32_e32 v68, v69, v68
	v_add_f32_e32 v69, 1.0, v72
	v_rcp_f32_e32 v69, v69
	v_add_f32_e32 v72, 1.0, v73
	v_rcp_f32_e32 v72, v72
	v_mul_f32_e32 v65, v65, v68
	v_mul_f32_e32 v68, v70, v69
	v_mul_f32_e32 v66, v66, v68
	v_mul_f32_e32 v68, v71, v72
	v_cvt_pk_bf16_f32 v64, v64, v65
	v_mul_f32_e32 v67, v67, v68
	v_cvt_pk_bf16_f32 v65, v66, v67
	global_store_dwordx2 v[80:81], v[64:65], off offset:128
	v_mul_f32_e32 v64, 0xbfb8aa3b, v60
	v_exp_f32_e32 v66, v64
	v_mul_f32_e32 v67, 0xbfb8aa3b, v61
	v_exp_f32_e32 v67, v67
	v_add_f32_e32 v66, 1.0, v66
	v_rcp_f32_e32 v66, v66
	v_lshl_add_u64 v[64:65], v[80:81], 0, s[100:101]
	v_mul_f32_e32 v60, v60, v66
	v_mul_f32_e32 v56, v56, v60
	v_add_f32_e32 v60, 1.0, v67
	v_mul_f32_e32 v66, 0xbfb8aa3b, v62
	v_rcp_f32_e32 v60, v60
	v_exp_f32_e32 v66, v66
	v_mul_f32_e32 v67, 0xbfb8aa3b, v63
	v_exp_f32_e32 v67, v67
	v_mul_f32_e32 v60, v61, v60
	v_add_f32_e32 v61, 1.0, v66
	v_rcp_f32_e32 v61, v61
	v_add_f32_e32 v66, 1.0, v67
	v_rcp_f32_e32 v66, v66
	v_mul_f32_e32 v57, v57, v60
	v_mul_f32_e32 v60, v62, v61
	v_mul_f32_e32 v61, 0xbfb8aa3b, v52
	v_exp_f32_e32 v61, v61
	v_mul_f32_e32 v58, v58, v60
	v_mul_f32_e32 v60, v63, v66
	v_mul_f32_e32 v59, v59, v60
	v_cvt_pk_bf16_f32 v56, v56, v57
	v_cvt_pk_bf16_f32 v57, v58, v59
	v_add_f32_e32 v58, 1.0, v61
	v_rcp_f32_e32 v58, v58
	v_mul_f32_e32 v59, 0xbfb8aa3b, v53
	v_exp_f32_e32 v59, v59
	global_store_dwordx2 v[64:65], v[56:57], off
	v_mul_f32_e32 v52, v52, v58
	v_mul_f32_e32 v48, v48, v52
	v_add_f32_e32 v52, 1.0, v59
	v_mul_f32_e32 v56, 0xbfb8aa3b, v54
	v_rcp_f32_e32 v52, v52
	v_exp_f32_e32 v56, v56
	v_mul_f32_e32 v57, 0xbfb8aa3b, v55
	v_exp_f32_e32 v57, v57
	v_mul_f32_e32 v52, v53, v52
	v_add_f32_e32 v53, 1.0, v56
	v_rcp_f32_e32 v53, v53
	v_add_f32_e32 v56, 1.0, v57
	v_rcp_f32_e32 v56, v56
	v_mul_f32_e32 v49, v49, v52
	v_mul_f32_e32 v52, v54, v53
	v_mul_f32_e32 v50, v50, v52
	v_mul_f32_e32 v52, v55, v56
	v_cvt_pk_bf16_f32 v48, v48, v49
	v_mul_f32_e32 v51, v51, v52
	v_cvt_pk_bf16_f32 v49, v50, v51
	global_store_dwordx2 v[64:65], v[48:49], off offset:128
	v_mul_f32_e32 v48, 0xbfb8aa3b, v44
	v_exp_f32_e32 v50, v48
	v_mul_f32_e32 v51, 0xbfb8aa3b, v45
	v_exp_f32_e32 v51, v51
	v_add_f32_e32 v50, 1.0, v50
	v_rcp_f32_e32 v50, v50
	v_lshl_add_u64 v[48:49], v[64:65], 0, s[98:99]
	v_mul_f32_e32 v44, v44, v50
	v_mul_f32_e32 v40, v40, v44
	v_add_f32_e32 v44, 1.0, v51
	v_mul_f32_e32 v50, 0xbfb8aa3b, v46
	v_rcp_f32_e32 v44, v44
	v_exp_f32_e32 v50, v50
	v_mul_f32_e32 v51, 0xbfb8aa3b, v47
	v_exp_f32_e32 v51, v51
	v_mul_f32_e32 v44, v45, v44
	v_add_f32_e32 v45, 1.0, v50
	v_rcp_f32_e32 v45, v45
	v_add_f32_e32 v50, 1.0, v51
	v_rcp_f32_e32 v50, v50
	v_mul_f32_e32 v41, v41, v44
	v_mul_f32_e32 v44, v46, v45
	v_mul_f32_e32 v45, 0xbfb8aa3b, v36
	v_exp_f32_e32 v45, v45
	v_mul_f32_e32 v42, v42, v44
	v_mul_f32_e32 v44, v47, v50
	v_mul_f32_e32 v43, v43, v44
	v_cvt_pk_bf16_f32 v40, v40, v41
	v_cvt_pk_bf16_f32 v41, v42, v43
	v_add_f32_e32 v42, 1.0, v45
	v_rcp_f32_e32 v42, v42
	v_mul_f32_e32 v43, 0xbfb8aa3b, v37
	v_exp_f32_e32 v43, v43
	global_store_dwordx2 v[48:49], v[40:41], off
	v_mul_f32_e32 v36, v36, v42
	v_mul_f32_e32 v32, v32, v36
	v_add_f32_e32 v36, 1.0, v43
	v_mul_f32_e32 v40, 0xbfb8aa3b, v38
	v_rcp_f32_e32 v36, v36
	v_exp_f32_e32 v40, v40
	v_mul_f32_e32 v41, 0xbfb8aa3b, v39
	v_exp_f32_e32 v41, v41
	v_mul_f32_e32 v36, v37, v36
	v_add_f32_e32 v37, 1.0, v40
	v_rcp_f32_e32 v37, v37
	v_add_f32_e32 v40, 1.0, v41
	v_rcp_f32_e32 v40, v40
	v_mul_f32_e32 v33, v33, v36
	v_mul_f32_e32 v36, v38, v37
	v_mul_f32_e32 v34, v34, v36
	v_mul_f32_e32 v36, v39, v40
	v_cvt_pk_bf16_f32 v32, v32, v33
	v_mul_f32_e32 v35, v35, v36
	v_cvt_pk_bf16_f32 v33, v34, v35
	global_store_dwordx2 v[48:49], v[32:33], off offset:128
	v_mul_f32_e32 v32, 0xbfb8aa3b, v28
	v_exp_f32_e32 v34, v32
	v_mul_f32_e32 v35, 0xbfb8aa3b, v29
	v_exp_f32_e32 v35, v35
	v_add_f32_e32 v34, 1.0, v34
	v_rcp_f32_e32 v34, v34
	v_lshl_add_u64 v[32:33], v[48:49], 0, s[98:99]
	v_mul_f32_e32 v28, v28, v34
	v_mul_f32_e32 v24, v24, v28
	v_add_f32_e32 v28, 1.0, v35
	v_mul_f32_e32 v34, 0xbfb8aa3b, v30
	v_rcp_f32_e32 v28, v28
	v_exp_f32_e32 v34, v34
	v_mul_f32_e32 v35, 0xbfb8aa3b, v31
	v_exp_f32_e32 v35, v35
	v_mul_f32_e32 v28, v29, v28
	v_add_f32_e32 v29, 1.0, v34
	v_rcp_f32_e32 v29, v29
	v_add_f32_e32 v34, 1.0, v35
	v_rcp_f32_e32 v34, v34
	v_mul_f32_e32 v25, v25, v28
	v_mul_f32_e32 v28, v30, v29
	v_mul_f32_e32 v29, 0xbfb8aa3b, v20
	v_exp_f32_e32 v29, v29
	v_mul_f32_e32 v26, v26, v28
	v_mul_f32_e32 v28, v31, v34
	v_mul_f32_e32 v27, v27, v28
	v_cvt_pk_bf16_f32 v24, v24, v25
	v_cvt_pk_bf16_f32 v25, v26, v27
	v_add_f32_e32 v26, 1.0, v29
	v_rcp_f32_e32 v26, v26
	v_mul_f32_e32 v27, 0xbfb8aa3b, v21
	v_exp_f32_e32 v27, v27
	global_store_dwordx2 v[32:33], v[24:25], off
	v_mul_f32_e32 v20, v20, v26
	v_mul_f32_e32 v16, v16, v20
	v_add_f32_e32 v20, 1.0, v27
	v_mul_f32_e32 v24, 0xbfb8aa3b, v22
	v_rcp_f32_e32 v20, v20
	v_exp_f32_e32 v24, v24
	v_mul_f32_e32 v25, 0xbfb8aa3b, v23
	v_exp_f32_e32 v25, v25
	v_mul_f32_e32 v20, v21, v20
	v_add_f32_e32 v21, 1.0, v24
	v_rcp_f32_e32 v21, v21
	v_add_f32_e32 v24, 1.0, v25
	v_rcp_f32_e32 v24, v24
	v_mul_f32_e32 v17, v17, v20
	v_mul_f32_e32 v20, v22, v21
	v_mul_f32_e32 v18, v18, v20
	v_mul_f32_e32 v20, v23, v24
	v_cvt_pk_bf16_f32 v16, v16, v17
	v_mul_f32_e32 v19, v19, v20
	v_cvt_pk_bf16_f32 v17, v18, v19
	global_store_dwordx2 v[32:33], v[16:17], off offset:128
	v_mul_f32_e32 v16, 0xbfb8aa3b, v12
	v_exp_f32_e32 v18, v16
	v_mul_f32_e32 v19, 0xbfb8aa3b, v13
	v_exp_f32_e32 v19, v19
	v_add_f32_e32 v18, 1.0, v18
	v_rcp_f32_e32 v18, v18
	v_lshl_add_u64 v[16:17], v[32:33], 0, s[98:99]
	v_mul_f32_e32 v12, v12, v18
	v_mul_f32_e32 v8, v8, v12
	v_add_f32_e32 v12, 1.0, v19
	v_mul_f32_e32 v18, 0xbfb8aa3b, v14
	v_rcp_f32_e32 v12, v12
	v_exp_f32_e32 v18, v18
	v_mul_f32_e32 v19, 0xbfb8aa3b, v15
	v_exp_f32_e32 v19, v19
	v_mul_f32_e32 v12, v13, v12
	v_add_f32_e32 v13, 1.0, v18
	v_rcp_f32_e32 v13, v13
	v_add_f32_e32 v18, 1.0, v19
	v_rcp_f32_e32 v18, v18
	v_mul_f32_e32 v9, v9, v12
	v_mul_f32_e32 v12, v14, v13
	v_mul_f32_e32 v13, 0xbfb8aa3b, v4
	v_exp_f32_e32 v13, v13
	v_mul_f32_e32 v10, v10, v12
	v_mul_f32_e32 v12, v15, v18
	v_mul_f32_e32 v11, v11, v12
	v_cvt_pk_bf16_f32 v8, v8, v9
	v_cvt_pk_bf16_f32 v9, v10, v11
	v_add_f32_e32 v10, 1.0, v13
	v_rcp_f32_e32 v10, v10
	v_mul_f32_e32 v11, 0xbfb8aa3b, v5
	v_exp_f32_e32 v11, v11
	global_store_dwordx2 v[16:17], v[8:9], off
	v_mul_f32_e32 v4, v4, v10
	v_mul_f32_e32 v0, v0, v4
	v_add_f32_e32 v4, 1.0, v11
	v_mul_f32_e32 v8, 0xbfb8aa3b, v6
	v_rcp_f32_e32 v4, v4
	v_exp_f32_e32 v8, v8
	v_mul_f32_e32 v9, 0xbfb8aa3b, v7
	v_exp_f32_e32 v9, v9
	v_mul_f32_e32 v4, v5, v4
	v_add_f32_e32 v5, 1.0, v8
	v_rcp_f32_e32 v5, v5
	v_add_f32_e32 v8, 1.0, v9
	v_rcp_f32_e32 v8, v8
	v_mul_f32_e32 v1, v1, v4
	v_mul_f32_e32 v4, v6, v5
	v_mul_f32_e32 v2, v2, v4
	v_mul_f32_e32 v4, v7, v8
	s_andn2_b64 vcc, exec, s[10:11]
	s_mov_b64 s[10:11], -1
	v_mul_f32_e32 v3, v3, v4
	v_cvt_pk_bf16_f32 v0, v0, v1
	v_cvt_pk_bf16_f32 v1, v2, v3
	global_store_dwordx2 v[16:17], v[0:1], off offset:128
	s_cbranch_vccnz .LBB0_720
	s_andn2_b64 vcc, exec, s[0:1]
	s_cbranch_vccnz .LBB0_719
	s_barrier
	s_branch .LBB0_719

.LBB0_954:
	s_mov_b64 s[98:99], 0x16000
	s_mov_b64 s[100:101], 0x6e000
	v_mul_f32_e32 v151, 0xbfb8aa3b, v124
	v_exp_f32_e32 v151, v151
	v_mul_f32_e32 v154, 0xbfb8aa3b, v125
	v_exp_f32_e32 v154, v154
	v_lshl_or_b32 v142, s71, 7, v146
	v_add_f32_e32 v151, 1.0, v151
	v_rcp_f32_e32 v151, v151
	v_lshl_add_u32 v150, s48, 8, v144
	v_ashrrev_i32_e32 v143, 31, v142
	v_mov_b64_e32 v[140:141], s[22:23]
	v_mul_f32_e32 v124, v124, v151
	v_mul_f32_e32 v120, v120, v124
	v_add_f32_e32 v124, 1.0, v154
	v_mul_f32_e32 v151, 0xbfb8aa3b, v126
	v_rcp_f32_e32 v124, v124
	v_exp_f32_e32 v151, v151
	v_mul_f32_e32 v154, 0xbfb8aa3b, v127
	v_exp_f32_e32 v154, v154
	v_mul_f32_e32 v124, v125, v124
	v_add_f32_e32 v125, 1.0, v151
	v_rcp_f32_e32 v125, v125
	v_add_f32_e32 v151, 1.0, v154
	v_rcp_f32_e32 v151, v151
	v_mul_f32_e32 v121, v121, v124
	v_mul_f32_e32 v124, v126, v125
	v_mul_f32_e32 v125, 0xbfb8aa3b, v116
	v_exp_f32_e32 v125, v125
	v_mul_f32_e32 v122, v122, v124
	v_mul_f32_e32 v124, v127, v151
	v_mul_f32_e32 v123, v123, v124
	v_cvt_pk_bf16_f32 v120, v120, v121
	v_cvt_pk_bf16_f32 v121, v122, v123
	v_add_f32_e32 v122, 1.0, v125
	v_rcp_f32_e32 v122, v122
	v_mul_f32_e32 v123, 0xbfb8aa3b, v117
	v_exp_f32_e32 v123, v123
	v_mad_i64_i32 v[152:153], s[52:53], v150, s70, v[140:141]
	v_lshlrev_b64 v[142:143], 1, v[142:143]
	v_lshl_add_u64 v[152:153], v[152:153], 0, v[142:143]
	v_mul_f32_e32 v116, v116, v122
	global_store_dwordx2 v[152:153], v[120:121], off
	v_mul_f32_e32 v112, v112, v116
	v_add_f32_e32 v116, 1.0, v123
	v_mul_f32_e32 v120, 0xbfb8aa3b, v118
	v_rcp_f32_e32 v116, v116
	v_exp_f32_e32 v120, v120
	v_mul_f32_e32 v121, 0xbfb8aa3b, v119
	v_exp_f32_e32 v121, v121
	v_mul_f32_e32 v116, v117, v116
	v_add_f32_e32 v117, 1.0, v120
	v_rcp_f32_e32 v117, v117
	v_add_f32_e32 v120, 1.0, v121
	v_rcp_f32_e32 v120, v120
	v_mul_f32_e32 v113, v113, v116
	v_mul_f32_e32 v116, v118, v117
	v_mul_f32_e32 v114, v114, v116
	v_mul_f32_e32 v116, v119, v120
	v_cvt_pk_bf16_f32 v112, v112, v113
	v_mul_f32_e32 v115, v115, v116
	v_cvt_pk_bf16_f32 v113, v114, v115
	global_store_dwordx2 v[152:153], v[112:113], off offset:128
	v_mul_f32_e32 v112, 0xbfb8aa3b, v108
	v_exp_f32_e32 v114, v112
	v_mul_f32_e32 v115, 0xbfb8aa3b, v109
	v_exp_f32_e32 v115, v115
	v_add_f32_e32 v114, 1.0, v114
	v_rcp_f32_e32 v114, v114
	v_lshl_add_u64 v[112:113], v[152:153], 0, s[98:99]
	v_mul_f32_e32 v108, v108, v114
	v_mul_f32_e32 v104, v104, v108
	v_add_f32_e32 v108, 1.0, v115
	v_mul_f32_e32 v114, 0xbfb8aa3b, v110
	v_rcp_f32_e32 v108, v108
	v_exp_f32_e32 v114, v114
	v_mul_f32_e32 v115, 0xbfb8aa3b, v111
	v_exp_f32_e32 v115, v115
	v_mul_f32_e32 v108, v109, v108
	v_add_f32_e32 v109, 1.0, v114
	v_rcp_f32_e32 v109, v109
	v_add_f32_e32 v114, 1.0, v115
	v_rcp_f32_e32 v114, v114
	v_mul_f32_e32 v105, v105, v108
	v_mul_f32_e32 v108, v110, v109
	v_mul_f32_e32 v109, 0xbfb8aa3b, v100
	v_exp_f32_e32 v109, v109
	v_mul_f32_e32 v106, v106, v108
	v_mul_f32_e32 v108, v111, v114
	v_mul_f32_e32 v107, v107, v108
	v_cvt_pk_bf16_f32 v104, v104, v105
	v_cvt_pk_bf16_f32 v105, v106, v107
	v_add_f32_e32 v106, 1.0, v109
	v_rcp_f32_e32 v106, v106
	v_mul_f32_e32 v107, 0xbfb8aa3b, v101
	v_exp_f32_e32 v107, v107
	global_store_dwordx2 v[112:113], v[104:105], off
	v_mul_f32_e32 v100, v100, v106
	v_mul_f32_e32 v96, v96, v100
	v_add_f32_e32 v100, 1.0, v107
	v_mul_f32_e32 v104, 0xbfb8aa3b, v102
	v_rcp_f32_e32 v100, v100
	v_exp_f32_e32 v104, v104
	v_mul_f32_e32 v105, 0xbfb8aa3b, v103
	v_exp_f32_e32 v105, v105
	v_mul_f32_e32 v100, v101, v100
	v_add_f32_e32 v101, 1.0, v104
	v_rcp_f32_e32 v101, v101
	v_add_f32_e32 v104, 1.0, v105
	v_rcp_f32_e32 v104, v104
	v_mul_f32_e32 v97, v97, v100
	v_mul_f32_e32 v100, v102, v101
	v_mul_f32_e32 v98, v98, v100
	v_mul_f32_e32 v100, v103, v104
	v_cvt_pk_bf16_f32 v96, v96, v97
	v_mul_f32_e32 v99, v99, v100
	v_cvt_pk_bf16_f32 v97, v98, v99
	global_store_dwordx2 v[112:113], v[96:97], off offset:128
	v_mul_f32_e32 v96, 0xbfb8aa3b, v92
	v_exp_f32_e32 v98, v96
	v_mul_f32_e32 v99, 0xbfb8aa3b, v93
	v_exp_f32_e32 v99, v99
	v_add_f32_e32 v98, 1.0, v98
	v_rcp_f32_e32 v98, v98
	v_lshl_add_u64 v[96:97], v[112:113], 0, s[98:99]
	v_mul_f32_e32 v92, v92, v98
	v_mul_f32_e32 v88, v88, v92
	v_add_f32_e32 v92, 1.0, v99
	v_mul_f32_e32 v98, 0xbfb8aa3b, v94
	v_rcp_f32_e32 v92, v92
	v_exp_f32_e32 v98, v98
	v_mul_f32_e32 v99, 0xbfb8aa3b, v95
	v_exp_f32_e32 v99, v99
	v_mul_f32_e32 v92, v93, v92
	v_add_f32_e32 v93, 1.0, v98
	v_rcp_f32_e32 v93, v93
	v_add_f32_e32 v98, 1.0, v99
	v_rcp_f32_e32 v98, v98
	v_mul_f32_e32 v89, v89, v92
	v_mul_f32_e32 v92, v94, v93
	v_mul_f32_e32 v93, 0xbfb8aa3b, v84
	v_exp_f32_e32 v93, v93
	v_mul_f32_e32 v90, v90, v92
	v_mul_f32_e32 v92, v95, v98
	v_mul_f32_e32 v91, v91, v92
	v_cvt_pk_bf16_f32 v88, v88, v89
	v_cvt_pk_bf16_f32 v89, v90, v91
	v_add_f32_e32 v90, 1.0, v93
	v_rcp_f32_e32 v90, v90
	v_mul_f32_e32 v91, 0xbfb8aa3b, v85
	v_exp_f32_e32 v91, v91
	global_store_dwordx2 v[96:97], v[88:89], off
	v_mul_f32_e32 v84, v84, v90
	v_mul_f32_e32 v80, v80, v84
	v_add_f32_e32 v84, 1.0, v91
	v_mul_f32_e32 v88, 0xbfb8aa3b, v86
	v_rcp_f32_e32 v84, v84
	v_exp_f32_e32 v88, v88
	v_mul_f32_e32 v89, 0xbfb8aa3b, v87
	v_exp_f32_e32 v89, v89
	v_mul_f32_e32 v84, v85, v84
	v_add_f32_e32 v85, 1.0, v88
	v_rcp_f32_e32 v85, v85
	v_add_f32_e32 v88, 1.0, v89
	v_rcp_f32_e32 v88, v88
	v_mul_f32_e32 v81, v81, v84
	v_mul_f32_e32 v84, v86, v85
	v_mul_f32_e32 v82, v82, v84
	v_mul_f32_e32 v84, v87, v88
	v_cvt_pk_bf16_f32 v80, v80, v81
	v_mul_f32_e32 v83, v83, v84
	v_cvt_pk_bf16_f32 v81, v82, v83
	global_store_dwordx2 v[96:97], v[80:81], off offset:128
	v_mul_f32_e32 v80, 0xbfb8aa3b, v76
	v_exp_f32_e32 v82, v80
	v_mul_f32_e32 v83, 0xbfb8aa3b, v77
	v_exp_f32_e32 v83, v83
	v_add_f32_e32 v82, 1.0, v82
	v_rcp_f32_e32 v82, v82
	v_lshl_add_u64 v[80:81], v[96:97], 0, s[98:99]
	v_mul_f32_e32 v76, v76, v82
	v_mul_f32_e32 v72, v72, v76
	v_add_f32_e32 v76, 1.0, v83
	v_mul_f32_e32 v82, 0xbfb8aa3b, v78
	v_rcp_f32_e32 v76, v76
	v_exp_f32_e32 v82, v82
	v_mul_f32_e32 v83, 0xbfb8aa3b, v79
	v_exp_f32_e32 v83, v83
	v_mul_f32_e32 v76, v77, v76
	v_add_f32_e32 v77, 1.0, v82
	v_rcp_f32_e32 v77, v77
	v_add_f32_e32 v82, 1.0, v83
	v_rcp_f32_e32 v82, v82
	v_mul_f32_e32 v73, v73, v76
	v_mul_f32_e32 v76, v78, v77
	v_mul_f32_e32 v77, 0xbfb8aa3b, v68
	v_exp_f32_e32 v77, v77
	v_mul_f32_e32 v74, v74, v76
	v_mul_f32_e32 v76, v79, v82
	v_mul_f32_e32 v75, v75, v76
	v_cvt_pk_bf16_f32 v72, v72, v73
	v_cvt_pk_bf16_f32 v73, v74, v75
	v_add_f32_e32 v74, 1.0, v77
	v_rcp_f32_e32 v74, v74
	v_mul_f32_e32 v75, 0xbfb8aa3b, v69
	v_exp_f32_e32 v75, v75
	global_store_dwordx2 v[80:81], v[72:73], off
	v_mul_f32_e32 v68, v68, v74
	v_mul_f32_e32 v64, v64, v68
	v_add_f32_e32 v68, 1.0, v75
	v_mul_f32_e32 v72, 0xbfb8aa3b, v70
	v_rcp_f32_e32 v68, v68
	v_exp_f32_e32 v72, v72
	v_mul_f32_e32 v73, 0xbfb8aa3b, v71
	v_exp_f32_e32 v73, v73
	v_mul_f32_e32 v68, v69, v68
	v_add_f32_e32 v69, 1.0, v72
	v_rcp_f32_e32 v69, v69
	v_add_f32_e32 v72, 1.0, v73
	v_rcp_f32_e32 v72, v72
	v_mul_f32_e32 v65, v65, v68
	v_mul_f32_e32 v68, v70, v69
	v_mul_f32_e32 v66, v66, v68
	v_mul_f32_e32 v68, v71, v72
	v_cvt_pk_bf16_f32 v64, v64, v65
	v_mul_f32_e32 v67, v67, v68
	v_cvt_pk_bf16_f32 v65, v66, v67
	global_store_dwordx2 v[80:81], v[64:65], off offset:128
	v_mul_f32_e32 v64, 0xbfb8aa3b, v60
	v_exp_f32_e32 v66, v64
	v_mul_f32_e32 v67, 0xbfb8aa3b, v61
	v_exp_f32_e32 v67, v67
	v_add_f32_e32 v66, 1.0, v66
	v_rcp_f32_e32 v66, v66
	v_lshl_add_u64 v[64:65], v[80:81], 0, s[100:101]
	v_mul_f32_e32 v60, v60, v66
	v_mul_f32_e32 v56, v56, v60
	v_add_f32_e32 v60, 1.0, v67
	v_mul_f32_e32 v66, 0xbfb8aa3b, v62
	v_rcp_f32_e32 v60, v60
	v_exp_f32_e32 v66, v66
	v_mul_f32_e32 v67, 0xbfb8aa3b, v63
	v_exp_f32_e32 v67, v67
	v_mul_f32_e32 v60, v61, v60
	v_add_f32_e32 v61, 1.0, v66
	v_rcp_f32_e32 v61, v61
	v_add_f32_e32 v66, 1.0, v67
	v_rcp_f32_e32 v66, v66
	v_mul_f32_e32 v57, v57, v60
	v_mul_f32_e32 v60, v62, v61
	v_mul_f32_e32 v61, 0xbfb8aa3b, v52
	v_exp_f32_e32 v61, v61
	v_mul_f32_e32 v58, v58, v60
	v_mul_f32_e32 v60, v63, v66
	v_mul_f32_e32 v59, v59, v60
	v_cvt_pk_bf16_f32 v56, v56, v57
	v_cvt_pk_bf16_f32 v57, v58, v59
	v_add_f32_e32 v58, 1.0, v61
	v_rcp_f32_e32 v58, v58
	v_mul_f32_e32 v59, 0xbfb8aa3b, v53
	v_exp_f32_e32 v59, v59
	global_store_dwordx2 v[64:65], v[56:57], off
	v_mul_f32_e32 v52, v52, v58
	v_mul_f32_e32 v48, v48, v52
	v_add_f32_e32 v52, 1.0, v59
	v_mul_f32_e32 v56, 0xbfb8aa3b, v54
	v_rcp_f32_e32 v52, v52
	v_exp_f32_e32 v56, v56
	v_mul_f32_e32 v57, 0xbfb8aa3b, v55
	v_exp_f32_e32 v57, v57
	v_mul_f32_e32 v52, v53, v52
	v_add_f32_e32 v53, 1.0, v56
	v_rcp_f32_e32 v53, v53
	v_add_f32_e32 v56, 1.0, v57
	v_rcp_f32_e32 v56, v56
	v_mul_f32_e32 v49, v49, v52
	v_mul_f32_e32 v52, v54, v53
	v_mul_f32_e32 v50, v50, v52
	v_mul_f32_e32 v52, v55, v56
	v_cvt_pk_bf16_f32 v48, v48, v49
	v_mul_f32_e32 v51, v51, v52
	v_cvt_pk_bf16_f32 v49, v50, v51
	global_store_dwordx2 v[64:65], v[48:49], off offset:128
	v_mul_f32_e32 v48, 0xbfb8aa3b, v44
	v_exp_f32_e32 v50, v48
	v_mul_f32_e32 v51, 0xbfb8aa3b, v45
	v_exp_f32_e32 v51, v51
	v_add_f32_e32 v50, 1.0, v50
	v_rcp_f32_e32 v50, v50
	v_lshl_add_u64 v[48:49], v[64:65], 0, s[98:99]
	v_mul_f32_e32 v44, v44, v50
	v_mul_f32_e32 v40, v40, v44
	v_add_f32_e32 v44, 1.0, v51
	v_mul_f32_e32 v50, 0xbfb8aa3b, v46
	v_rcp_f32_e32 v44, v44
	v_exp_f32_e32 v50, v50
	v_mul_f32_e32 v51, 0xbfb8aa3b, v47
	v_exp_f32_e32 v51, v51
	v_mul_f32_e32 v44, v45, v44
	v_add_f32_e32 v45, 1.0, v50
	v_rcp_f32_e32 v45, v45
	v_add_f32_e32 v50, 1.0, v51
	v_rcp_f32_e32 v50, v50
	v_mul_f32_e32 v41, v41, v44
	v_mul_f32_e32 v44, v46, v45
	v_mul_f32_e32 v45, 0xbfb8aa3b, v36
	v_exp_f32_e32 v45, v45
	v_mul_f32_e32 v42, v42, v44
	v_mul_f32_e32 v44, v47, v50
	v_mul_f32_e32 v43, v43, v44
	v_cvt_pk_bf16_f32 v40, v40, v41
	v_cvt_pk_bf16_f32 v41, v42, v43
	v_add_f32_e32 v42, 1.0, v45
	v_rcp_f32_e32 v42, v42
	v_mul_f32_e32 v43, 0xbfb8aa3b, v37
	v_exp_f32_e32 v43, v43
	global_store_dwordx2 v[48:49], v[40:41], off
	v_mul_f32_e32 v36, v36, v42
	v_mul_f32_e32 v32, v32, v36
	v_add_f32_e32 v36, 1.0, v43
	v_mul_f32_e32 v40, 0xbfb8aa3b, v38
	v_rcp_f32_e32 v36, v36
	v_exp_f32_e32 v40, v40
	v_mul_f32_e32 v41, 0xbfb8aa3b, v39
	v_exp_f32_e32 v41, v41
	v_mul_f32_e32 v36, v37, v36
	v_add_f32_e32 v37, 1.0, v40
	v_rcp_f32_e32 v37, v37
	v_add_f32_e32 v40, 1.0, v41
	v_rcp_f32_e32 v40, v40
	v_mul_f32_e32 v33, v33, v36
	v_mul_f32_e32 v36, v38, v37
	v_mul_f32_e32 v34, v34, v36
	v_mul_f32_e32 v36, v39, v40
	v_cvt_pk_bf16_f32 v32, v32, v33
	v_mul_f32_e32 v35, v35, v36
	v_cvt_pk_bf16_f32 v33, v34, v35
	global_store_dwordx2 v[48:49], v[32:33], off offset:128
	v_mul_f32_e32 v32, 0xbfb8aa3b, v28
	v_exp_f32_e32 v34, v32
	v_mul_f32_e32 v35, 0xbfb8aa3b, v29
	v_exp_f32_e32 v35, v35
	v_add_f32_e32 v34, 1.0, v34
	v_rcp_f32_e32 v34, v34
	v_lshl_add_u64 v[32:33], v[48:49], 0, s[98:99]
	v_mul_f32_e32 v28, v28, v34
	v_mul_f32_e32 v24, v24, v28
	v_add_f32_e32 v28, 1.0, v35
	v_mul_f32_e32 v34, 0xbfb8aa3b, v30
	v_rcp_f32_e32 v28, v28
	v_exp_f32_e32 v34, v34
	v_mul_f32_e32 v35, 0xbfb8aa3b, v31
	v_exp_f32_e32 v35, v35
	v_mul_f32_e32 v28, v29, v28
	v_add_f32_e32 v29, 1.0, v34
	v_rcp_f32_e32 v29, v29
	v_add_f32_e32 v34, 1.0, v35
	v_rcp_f32_e32 v34, v34
	v_mul_f32_e32 v25, v25, v28
	v_mul_f32_e32 v28, v30, v29
	v_mul_f32_e32 v29, 0xbfb8aa3b, v20
	v_exp_f32_e32 v29, v29
	v_mul_f32_e32 v26, v26, v28
	v_mul_f32_e32 v28, v31, v34
	v_mul_f32_e32 v27, v27, v28
	v_cvt_pk_bf16_f32 v24, v24, v25
	v_cvt_pk_bf16_f32 v25, v26, v27
	v_add_f32_e32 v26, 1.0, v29
	v_rcp_f32_e32 v26, v26
	v_mul_f32_e32 v27, 0xbfb8aa3b, v21
	v_exp_f32_e32 v27, v27
	global_store_dwordx2 v[32:33], v[24:25], off
	v_mul_f32_e32 v20, v20, v26
	v_mul_f32_e32 v16, v16, v20
	v_add_f32_e32 v20, 1.0, v27
	v_mul_f32_e32 v24, 0xbfb8aa3b, v22
	v_rcp_f32_e32 v20, v20
	v_exp_f32_e32 v24, v24
	v_mul_f32_e32 v25, 0xbfb8aa3b, v23
	v_exp_f32_e32 v25, v25
	v_mul_f32_e32 v20, v21, v20
	v_add_f32_e32 v21, 1.0, v24
	v_rcp_f32_e32 v21, v21
	v_add_f32_e32 v24, 1.0, v25
	v_rcp_f32_e32 v24, v24
	v_mul_f32_e32 v17, v17, v20
	v_mul_f32_e32 v20, v22, v21
	v_mul_f32_e32 v18, v18, v20
	v_mul_f32_e32 v20, v23, v24
	v_cvt_pk_bf16_f32 v16, v16, v17
	v_mul_f32_e32 v19, v19, v20
	v_cvt_pk_bf16_f32 v17, v18, v19
	global_store_dwordx2 v[32:33], v[16:17], off offset:128
	v_mul_f32_e32 v16, 0xbfb8aa3b, v12
	v_exp_f32_e32 v18, v16
	v_mul_f32_e32 v19, 0xbfb8aa3b, v13
	v_exp_f32_e32 v19, v19
	v_add_f32_e32 v18, 1.0, v18
	v_rcp_f32_e32 v18, v18
	v_lshl_add_u64 v[16:17], v[32:33], 0, s[98:99]
	v_mul_f32_e32 v12, v12, v18
	v_mul_f32_e32 v8, v8, v12
	v_add_f32_e32 v12, 1.0, v19
	v_mul_f32_e32 v18, 0xbfb8aa3b, v14
	v_rcp_f32_e32 v12, v12
	v_exp_f32_e32 v18, v18
	v_mul_f32_e32 v19, 0xbfb8aa3b, v15
	v_exp_f32_e32 v19, v19
	v_mul_f32_e32 v12, v13, v12
	v_add_f32_e32 v13, 1.0, v18
	v_rcp_f32_e32 v13, v13
	v_add_f32_e32 v18, 1.0, v19
	v_rcp_f32_e32 v18, v18
	v_mul_f32_e32 v9, v9, v12
	v_mul_f32_e32 v12, v14, v13
	v_mul_f32_e32 v13, 0xbfb8aa3b, v4
	v_exp_f32_e32 v13, v13
	v_mul_f32_e32 v10, v10, v12
	v_mul_f32_e32 v12, v15, v18
	v_mul_f32_e32 v11, v11, v12
	v_cvt_pk_bf16_f32 v8, v8, v9
	v_cvt_pk_bf16_f32 v9, v10, v11
	v_add_f32_e32 v10, 1.0, v13
	v_rcp_f32_e32 v10, v10
	v_mul_f32_e32 v11, 0xbfb8aa3b, v5
	v_exp_f32_e32 v11, v11
	global_store_dwordx2 v[16:17], v[8:9], off
	v_mul_f32_e32 v4, v4, v10
	v_mul_f32_e32 v0, v0, v4
	v_add_f32_e32 v4, 1.0, v11
	v_mul_f32_e32 v8, 0xbfb8aa3b, v6
	v_rcp_f32_e32 v4, v4
	v_exp_f32_e32 v8, v8
	v_mul_f32_e32 v9, 0xbfb8aa3b, v7
	v_exp_f32_e32 v9, v9
	v_mul_f32_e32 v4, v5, v4
	v_add_f32_e32 v5, 1.0, v8
	v_rcp_f32_e32 v5, v5
	v_add_f32_e32 v8, 1.0, v9
	v_rcp_f32_e32 v8, v8
	v_mul_f32_e32 v1, v1, v4
	v_mul_f32_e32 v4, v6, v5
	v_mul_f32_e32 v2, v2, v4
	v_mul_f32_e32 v4, v7, v8
	s_andn2_b64 vcc, exec, s[10:11]
	s_mov_b64 s[10:11], -1
	v_mul_f32_e32 v3, v3, v4
	v_cvt_pk_bf16_f32 v0, v0, v1
	v_cvt_pk_bf16_f32 v1, v2, v3
	global_store_dwordx2 v[16:17], v[0:1], off offset:128
	s_cbranch_vccnz .LBB0_947
	s_andn2_b64 vcc, exec, s[0:1]
	s_cbranch_vccnz .LBB0_946
	s_barrier
	s_branch .LBB0_946

.LBB0_1437:
	s_mov_b64 s[98:99], 0x16000
	s_mov_b64 s[100:101], 0x6e000
	v_mul_f32_e32 v151, 0xbfb8aa3b, v124
	v_exp_f32_e32 v151, v151
	v_mul_f32_e32 v154, 0xbfb8aa3b, v125
	v_exp_f32_e32 v154, v154
	v_lshl_or_b32 v142, s65, 7, v146
	v_add_f32_e32 v151, 1.0, v151
	v_rcp_f32_e32 v151, v151
	v_lshl_add_u32 v150, s44, 8, v144
	v_ashrrev_i32_e32 v143, 31, v142
	v_mov_b64_e32 v[140:141], s[22:23]
	v_mul_f32_e32 v124, v124, v151
	v_mul_f32_e32 v120, v120, v124
	v_add_f32_e32 v124, 1.0, v154
	v_mul_f32_e32 v151, 0xbfb8aa3b, v126
	v_rcp_f32_e32 v124, v124
	v_exp_f32_e32 v151, v151
	v_mul_f32_e32 v154, 0xbfb8aa3b, v127
	v_exp_f32_e32 v154, v154
	v_mul_f32_e32 v124, v125, v124
	v_add_f32_e32 v125, 1.0, v151
	v_rcp_f32_e32 v125, v125
	v_add_f32_e32 v151, 1.0, v154
	v_rcp_f32_e32 v151, v151
	v_mul_f32_e32 v121, v121, v124
	v_mul_f32_e32 v124, v126, v125
	v_mul_f32_e32 v125, 0xbfb8aa3b, v116
	v_exp_f32_e32 v125, v125
	v_mul_f32_e32 v122, v122, v124
	v_mul_f32_e32 v124, v127, v151
	v_mul_f32_e32 v123, v123, v124
	v_cvt_pk_bf16_f32 v120, v120, v121
	v_cvt_pk_bf16_f32 v121, v122, v123
	v_add_f32_e32 v122, 1.0, v125
	v_rcp_f32_e32 v122, v122
	v_mul_f32_e32 v123, 0xbfb8aa3b, v117
	v_exp_f32_e32 v123, v123
	v_mad_i64_i32 v[152:153], s[46:47], v150, s64, v[140:141]
	v_lshlrev_b64 v[142:143], 1, v[142:143]
	v_lshl_add_u64 v[152:153], v[152:153], 0, v[142:143]
	v_mul_f32_e32 v116, v116, v122
	global_store_dwordx2 v[152:153], v[120:121], off
	v_mul_f32_e32 v112, v112, v116
	v_add_f32_e32 v116, 1.0, v123
	v_mul_f32_e32 v120, 0xbfb8aa3b, v118
	v_rcp_f32_e32 v116, v116
	v_exp_f32_e32 v120, v120
	v_mul_f32_e32 v121, 0xbfb8aa3b, v119
	v_exp_f32_e32 v121, v121
	v_mul_f32_e32 v116, v117, v116
	v_add_f32_e32 v117, 1.0, v120
	v_rcp_f32_e32 v117, v117
	v_add_f32_e32 v120, 1.0, v121
	v_rcp_f32_e32 v120, v120
	v_mul_f32_e32 v113, v113, v116
	v_mul_f32_e32 v116, v118, v117
	v_mul_f32_e32 v114, v114, v116
	v_mul_f32_e32 v116, v119, v120
	v_cvt_pk_bf16_f32 v112, v112, v113
	v_mul_f32_e32 v115, v115, v116
	v_cvt_pk_bf16_f32 v113, v114, v115
	global_store_dwordx2 v[152:153], v[112:113], off offset:128
	v_mul_f32_e32 v112, 0xbfb8aa3b, v108
	v_exp_f32_e32 v114, v112
	v_mul_f32_e32 v115, 0xbfb8aa3b, v109
	v_exp_f32_e32 v115, v115
	v_add_f32_e32 v114, 1.0, v114
	v_rcp_f32_e32 v114, v114
	v_lshl_add_u64 v[112:113], v[152:153], 0, s[98:99]
	v_mul_f32_e32 v108, v108, v114
	v_mul_f32_e32 v104, v104, v108
	v_add_f32_e32 v108, 1.0, v115
	v_mul_f32_e32 v114, 0xbfb8aa3b, v110
	v_rcp_f32_e32 v108, v108
	v_exp_f32_e32 v114, v114
	v_mul_f32_e32 v115, 0xbfb8aa3b, v111
	v_exp_f32_e32 v115, v115
	v_mul_f32_e32 v108, v109, v108
	v_add_f32_e32 v109, 1.0, v114
	v_rcp_f32_e32 v109, v109
	v_add_f32_e32 v114, 1.0, v115
	v_rcp_f32_e32 v114, v114
	v_mul_f32_e32 v105, v105, v108
	v_mul_f32_e32 v108, v110, v109
	v_mul_f32_e32 v109, 0xbfb8aa3b, v100
	v_exp_f32_e32 v109, v109
	v_mul_f32_e32 v106, v106, v108
	v_mul_f32_e32 v108, v111, v114
	v_mul_f32_e32 v107, v107, v108
	v_cvt_pk_bf16_f32 v104, v104, v105
	v_cvt_pk_bf16_f32 v105, v106, v107
	v_add_f32_e32 v106, 1.0, v109
	v_rcp_f32_e32 v106, v106
	v_mul_f32_e32 v107, 0xbfb8aa3b, v101
	v_exp_f32_e32 v107, v107
	global_store_dwordx2 v[112:113], v[104:105], off
	v_mul_f32_e32 v100, v100, v106
	v_mul_f32_e32 v96, v96, v100
	v_add_f32_e32 v100, 1.0, v107
	v_mul_f32_e32 v104, 0xbfb8aa3b, v102
	v_rcp_f32_e32 v100, v100
	v_exp_f32_e32 v104, v104
	v_mul_f32_e32 v105, 0xbfb8aa3b, v103
	v_exp_f32_e32 v105, v105
	v_mul_f32_e32 v100, v101, v100
	v_add_f32_e32 v101, 1.0, v104
	v_rcp_f32_e32 v101, v101
	v_add_f32_e32 v104, 1.0, v105
	v_rcp_f32_e32 v104, v104
	v_mul_f32_e32 v97, v97, v100
	v_mul_f32_e32 v100, v102, v101
	v_mul_f32_e32 v98, v98, v100
	v_mul_f32_e32 v100, v103, v104
	v_cvt_pk_bf16_f32 v96, v96, v97
	v_mul_f32_e32 v99, v99, v100
	v_cvt_pk_bf16_f32 v97, v98, v99
	global_store_dwordx2 v[112:113], v[96:97], off offset:128
	v_mul_f32_e32 v96, 0xbfb8aa3b, v92
	v_exp_f32_e32 v98, v96
	v_mul_f32_e32 v99, 0xbfb8aa3b, v93
	v_exp_f32_e32 v99, v99
	v_add_f32_e32 v98, 1.0, v98
	v_rcp_f32_e32 v98, v98
	v_lshl_add_u64 v[96:97], v[112:113], 0, s[98:99]
	v_mul_f32_e32 v92, v92, v98
	v_mul_f32_e32 v88, v88, v92
	v_add_f32_e32 v92, 1.0, v99
	v_mul_f32_e32 v98, 0xbfb8aa3b, v94
	v_rcp_f32_e32 v92, v92
	v_exp_f32_e32 v98, v98
	v_mul_f32_e32 v99, 0xbfb8aa3b, v95
	v_exp_f32_e32 v99, v99
	v_mul_f32_e32 v92, v93, v92
	v_add_f32_e32 v93, 1.0, v98
	v_rcp_f32_e32 v93, v93
	v_add_f32_e32 v98, 1.0, v99
	v_rcp_f32_e32 v98, v98
	v_mul_f32_e32 v89, v89, v92
	v_mul_f32_e32 v92, v94, v93
	v_mul_f32_e32 v93, 0xbfb8aa3b, v84
	v_exp_f32_e32 v93, v93
	v_mul_f32_e32 v90, v90, v92
	v_mul_f32_e32 v92, v95, v98
	v_mul_f32_e32 v91, v91, v92
	v_cvt_pk_bf16_f32 v88, v88, v89
	v_cvt_pk_bf16_f32 v89, v90, v91
	v_add_f32_e32 v90, 1.0, v93
	v_rcp_f32_e32 v90, v90
	v_mul_f32_e32 v91, 0xbfb8aa3b, v85
	v_exp_f32_e32 v91, v91
	global_store_dwordx2 v[96:97], v[88:89], off
	v_mul_f32_e32 v84, v84, v90
	v_mul_f32_e32 v80, v80, v84
	v_add_f32_e32 v84, 1.0, v91
	v_mul_f32_e32 v88, 0xbfb8aa3b, v86
	v_rcp_f32_e32 v84, v84
	v_exp_f32_e32 v88, v88
	v_mul_f32_e32 v89, 0xbfb8aa3b, v87
	v_exp_f32_e32 v89, v89
	v_mul_f32_e32 v84, v85, v84
	v_add_f32_e32 v85, 1.0, v88
	v_rcp_f32_e32 v85, v85
	v_add_f32_e32 v88, 1.0, v89
	v_rcp_f32_e32 v88, v88
	v_mul_f32_e32 v81, v81, v84
	v_mul_f32_e32 v84, v86, v85
	v_mul_f32_e32 v82, v82, v84
	v_mul_f32_e32 v84, v87, v88
	v_cvt_pk_bf16_f32 v80, v80, v81
	v_mul_f32_e32 v83, v83, v84
	v_cvt_pk_bf16_f32 v81, v82, v83
	global_store_dwordx2 v[96:97], v[80:81], off offset:128
	v_mul_f32_e32 v80, 0xbfb8aa3b, v76
	v_exp_f32_e32 v82, v80
	v_mul_f32_e32 v83, 0xbfb8aa3b, v77
	v_exp_f32_e32 v83, v83
	v_add_f32_e32 v82, 1.0, v82
	v_rcp_f32_e32 v82, v82
	v_lshl_add_u64 v[80:81], v[96:97], 0, s[98:99]
	v_mul_f32_e32 v76, v76, v82
	v_mul_f32_e32 v72, v72, v76
	v_add_f32_e32 v76, 1.0, v83
	v_mul_f32_e32 v82, 0xbfb8aa3b, v78
	v_rcp_f32_e32 v76, v76
	v_exp_f32_e32 v82, v82
	v_mul_f32_e32 v83, 0xbfb8aa3b, v79
	v_exp_f32_e32 v83, v83
	v_mul_f32_e32 v76, v77, v76
	v_add_f32_e32 v77, 1.0, v82
	v_rcp_f32_e32 v77, v77
	v_add_f32_e32 v82, 1.0, v83
	v_rcp_f32_e32 v82, v82
	v_mul_f32_e32 v73, v73, v76
	v_mul_f32_e32 v76, v78, v77
	v_mul_f32_e32 v77, 0xbfb8aa3b, v68
	v_exp_f32_e32 v77, v77
	v_mul_f32_e32 v74, v74, v76
	v_mul_f32_e32 v76, v79, v82
	v_mul_f32_e32 v75, v75, v76
	v_cvt_pk_bf16_f32 v72, v72, v73
	v_cvt_pk_bf16_f32 v73, v74, v75
	v_add_f32_e32 v74, 1.0, v77
	v_rcp_f32_e32 v74, v74
	v_mul_f32_e32 v75, 0xbfb8aa3b, v69
	v_exp_f32_e32 v75, v75
	global_store_dwordx2 v[80:81], v[72:73], off
	v_mul_f32_e32 v68, v68, v74
	v_mul_f32_e32 v64, v64, v68
	v_add_f32_e32 v68, 1.0, v75
	v_mul_f32_e32 v72, 0xbfb8aa3b, v70
	v_rcp_f32_e32 v68, v68
	v_exp_f32_e32 v72, v72
	v_mul_f32_e32 v73, 0xbfb8aa3b, v71
	v_exp_f32_e32 v73, v73
	v_mul_f32_e32 v68, v69, v68
	v_add_f32_e32 v69, 1.0, v72
	v_rcp_f32_e32 v69, v69
	v_add_f32_e32 v72, 1.0, v73
	v_rcp_f32_e32 v72, v72
	v_mul_f32_e32 v65, v65, v68
	v_mul_f32_e32 v68, v70, v69
	v_mul_f32_e32 v66, v66, v68
	v_mul_f32_e32 v68, v71, v72
	v_cvt_pk_bf16_f32 v64, v64, v65
	v_mul_f32_e32 v67, v67, v68
	v_cvt_pk_bf16_f32 v65, v66, v67
	global_store_dwordx2 v[80:81], v[64:65], off offset:128
	v_mul_f32_e32 v64, 0xbfb8aa3b, v60
	v_exp_f32_e32 v66, v64
	v_mul_f32_e32 v67, 0xbfb8aa3b, v61
	v_exp_f32_e32 v67, v67
	v_add_f32_e32 v66, 1.0, v66
	v_rcp_f32_e32 v66, v66
	v_lshl_add_u64 v[64:65], v[80:81], 0, s[100:101]
	v_mul_f32_e32 v60, v60, v66
	v_mul_f32_e32 v56, v56, v60
	v_add_f32_e32 v60, 1.0, v67
	v_mul_f32_e32 v66, 0xbfb8aa3b, v62
	v_rcp_f32_e32 v60, v60
	v_exp_f32_e32 v66, v66
	v_mul_f32_e32 v67, 0xbfb8aa3b, v63
	v_exp_f32_e32 v67, v67
	v_mul_f32_e32 v60, v61, v60
	v_add_f32_e32 v61, 1.0, v66
	v_rcp_f32_e32 v61, v61
	v_add_f32_e32 v66, 1.0, v67
	v_rcp_f32_e32 v66, v66
	v_mul_f32_e32 v57, v57, v60
	v_mul_f32_e32 v60, v62, v61
	v_mul_f32_e32 v61, 0xbfb8aa3b, v52
	v_exp_f32_e32 v61, v61
	v_mul_f32_e32 v58, v58, v60
	v_mul_f32_e32 v60, v63, v66
	v_mul_f32_e32 v59, v59, v60
	v_cvt_pk_bf16_f32 v56, v56, v57
	v_cvt_pk_bf16_f32 v57, v58, v59
	v_add_f32_e32 v58, 1.0, v61
	v_rcp_f32_e32 v58, v58
	v_mul_f32_e32 v59, 0xbfb8aa3b, v53
	v_exp_f32_e32 v59, v59
	global_store_dwordx2 v[64:65], v[56:57], off
	v_mul_f32_e32 v52, v52, v58
	v_mul_f32_e32 v48, v48, v52
	v_add_f32_e32 v52, 1.0, v59
	v_mul_f32_e32 v56, 0xbfb8aa3b, v54
	v_rcp_f32_e32 v52, v52
	v_exp_f32_e32 v56, v56
	v_mul_f32_e32 v57, 0xbfb8aa3b, v55
	v_exp_f32_e32 v57, v57
	v_mul_f32_e32 v52, v53, v52
	v_add_f32_e32 v53, 1.0, v56
	v_rcp_f32_e32 v53, v53
	v_add_f32_e32 v56, 1.0, v57
	v_rcp_f32_e32 v56, v56
	v_mul_f32_e32 v49, v49, v52
	v_mul_f32_e32 v52, v54, v53
	v_mul_f32_e32 v50, v50, v52
	v_mul_f32_e32 v52, v55, v56
	v_cvt_pk_bf16_f32 v48, v48, v49
	v_mul_f32_e32 v51, v51, v52
	v_cvt_pk_bf16_f32 v49, v50, v51
	global_store_dwordx2 v[64:65], v[48:49], off offset:128
	v_mul_f32_e32 v48, 0xbfb8aa3b, v44
	v_exp_f32_e32 v50, v48
	v_mul_f32_e32 v51, 0xbfb8aa3b, v45
	v_exp_f32_e32 v51, v51
	v_add_f32_e32 v50, 1.0, v50
	v_rcp_f32_e32 v50, v50
	v_lshl_add_u64 v[48:49], v[64:65], 0, s[98:99]
	v_mul_f32_e32 v44, v44, v50
	v_mul_f32_e32 v40, v40, v44
	v_add_f32_e32 v44, 1.0, v51
	v_mul_f32_e32 v50, 0xbfb8aa3b, v46
	v_rcp_f32_e32 v44, v44
	v_exp_f32_e32 v50, v50
	v_mul_f32_e32 v51, 0xbfb8aa3b, v47
	v_exp_f32_e32 v51, v51
	v_mul_f32_e32 v44, v45, v44
	v_add_f32_e32 v45, 1.0, v50
	v_rcp_f32_e32 v45, v45
	v_add_f32_e32 v50, 1.0, v51
	v_rcp_f32_e32 v50, v50
	v_mul_f32_e32 v41, v41, v44
	v_mul_f32_e32 v44, v46, v45
	v_mul_f32_e32 v45, 0xbfb8aa3b, v36
	v_exp_f32_e32 v45, v45
	v_mul_f32_e32 v42, v42, v44
	v_mul_f32_e32 v44, v47, v50
	v_mul_f32_e32 v43, v43, v44
	v_cvt_pk_bf16_f32 v40, v40, v41
	v_cvt_pk_bf16_f32 v41, v42, v43
	v_add_f32_e32 v42, 1.0, v45
	v_rcp_f32_e32 v42, v42
	v_mul_f32_e32 v43, 0xbfb8aa3b, v37
	v_exp_f32_e32 v43, v43
	global_store_dwordx2 v[48:49], v[40:41], off
	v_mul_f32_e32 v36, v36, v42
	v_mul_f32_e32 v32, v32, v36
	v_add_f32_e32 v36, 1.0, v43
	v_mul_f32_e32 v40, 0xbfb8aa3b, v38
	v_rcp_f32_e32 v36, v36
	v_exp_f32_e32 v40, v40
	v_mul_f32_e32 v41, 0xbfb8aa3b, v39
	v_exp_f32_e32 v41, v41
	v_mul_f32_e32 v36, v37, v36
	v_add_f32_e32 v37, 1.0, v40
	v_rcp_f32_e32 v37, v37
	v_add_f32_e32 v40, 1.0, v41
	v_rcp_f32_e32 v40, v40
	v_mul_f32_e32 v33, v33, v36
	v_mul_f32_e32 v36, v38, v37
	v_mul_f32_e32 v34, v34, v36
	v_mul_f32_e32 v36, v39, v40
	v_cvt_pk_bf16_f32 v32, v32, v33
	v_mul_f32_e32 v35, v35, v36
	v_cvt_pk_bf16_f32 v33, v34, v35
	global_store_dwordx2 v[48:49], v[32:33], off offset:128
	v_mul_f32_e32 v32, 0xbfb8aa3b, v28
	v_exp_f32_e32 v34, v32
	v_mul_f32_e32 v35, 0xbfb8aa3b, v29
	v_exp_f32_e32 v35, v35
	v_add_f32_e32 v34, 1.0, v34
	v_rcp_f32_e32 v34, v34
	v_lshl_add_u64 v[32:33], v[48:49], 0, s[98:99]
	v_mul_f32_e32 v28, v28, v34
	v_mul_f32_e32 v24, v24, v28
	v_add_f32_e32 v28, 1.0, v35
	v_mul_f32_e32 v34, 0xbfb8aa3b, v30
	v_rcp_f32_e32 v28, v28
	v_exp_f32_e32 v34, v34
	v_mul_f32_e32 v35, 0xbfb8aa3b, v31
	v_exp_f32_e32 v35, v35
	v_mul_f32_e32 v28, v29, v28
	v_add_f32_e32 v29, 1.0, v34
	v_rcp_f32_e32 v29, v29
	v_add_f32_e32 v34, 1.0, v35
	v_rcp_f32_e32 v34, v34
	v_mul_f32_e32 v25, v25, v28
	v_mul_f32_e32 v28, v30, v29
	v_mul_f32_e32 v29, 0xbfb8aa3b, v20
	v_exp_f32_e32 v29, v29
	v_mul_f32_e32 v26, v26, v28
	v_mul_f32_e32 v28, v31, v34
	v_mul_f32_e32 v27, v27, v28
	v_cvt_pk_bf16_f32 v24, v24, v25
	v_cvt_pk_bf16_f32 v25, v26, v27
	v_add_f32_e32 v26, 1.0, v29
	v_rcp_f32_e32 v26, v26
	v_mul_f32_e32 v27, 0xbfb8aa3b, v21
	v_exp_f32_e32 v27, v27
	global_store_dwordx2 v[32:33], v[24:25], off
	v_mul_f32_e32 v20, v20, v26
	v_mul_f32_e32 v16, v16, v20
	v_add_f32_e32 v20, 1.0, v27
	v_mul_f32_e32 v24, 0xbfb8aa3b, v22
	v_rcp_f32_e32 v20, v20
	v_exp_f32_e32 v24, v24
	v_mul_f32_e32 v25, 0xbfb8aa3b, v23
	v_exp_f32_e32 v25, v25
	v_mul_f32_e32 v20, v21, v20
	v_add_f32_e32 v21, 1.0, v24
	v_rcp_f32_e32 v21, v21
	v_add_f32_e32 v24, 1.0, v25
	v_rcp_f32_e32 v24, v24
	v_mul_f32_e32 v17, v17, v20
	v_mul_f32_e32 v20, v22, v21
	v_mul_f32_e32 v18, v18, v20
	v_mul_f32_e32 v20, v23, v24
	v_cvt_pk_bf16_f32 v16, v16, v17
	v_mul_f32_e32 v19, v19, v20
	v_cvt_pk_bf16_f32 v17, v18, v19
	global_store_dwordx2 v[32:33], v[16:17], off offset:128
	v_mul_f32_e32 v16, 0xbfb8aa3b, v12
	v_exp_f32_e32 v18, v16
	v_mul_f32_e32 v19, 0xbfb8aa3b, v13
	v_exp_f32_e32 v19, v19
	v_add_f32_e32 v18, 1.0, v18
	v_rcp_f32_e32 v18, v18
	v_lshl_add_u64 v[16:17], v[32:33], 0, s[98:99]
	v_mul_f32_e32 v12, v12, v18
	v_mul_f32_e32 v8, v8, v12
	v_add_f32_e32 v12, 1.0, v19
	v_mul_f32_e32 v18, 0xbfb8aa3b, v14
	v_rcp_f32_e32 v12, v12
	v_exp_f32_e32 v18, v18
	v_mul_f32_e32 v19, 0xbfb8aa3b, v15
	v_exp_f32_e32 v19, v19
	v_mul_f32_e32 v12, v13, v12
	v_add_f32_e32 v13, 1.0, v18
	v_rcp_f32_e32 v13, v13
	v_add_f32_e32 v18, 1.0, v19
	v_rcp_f32_e32 v18, v18
	v_mul_f32_e32 v9, v9, v12
	v_mul_f32_e32 v12, v14, v13
	v_mul_f32_e32 v13, 0xbfb8aa3b, v4
	v_exp_f32_e32 v13, v13
	v_mul_f32_e32 v10, v10, v12
	v_mul_f32_e32 v12, v15, v18
	v_mul_f32_e32 v11, v11, v12
	v_cvt_pk_bf16_f32 v8, v8, v9
	v_cvt_pk_bf16_f32 v9, v10, v11
	v_add_f32_e32 v10, 1.0, v13
	v_rcp_f32_e32 v10, v10
	v_mul_f32_e32 v11, 0xbfb8aa3b, v5
	v_exp_f32_e32 v11, v11
	global_store_dwordx2 v[16:17], v[8:9], off
	v_mul_f32_e32 v4, v4, v10
	v_mul_f32_e32 v0, v0, v4
	v_add_f32_e32 v4, 1.0, v11
	v_mul_f32_e32 v8, 0xbfb8aa3b, v6
	v_rcp_f32_e32 v4, v4
	v_exp_f32_e32 v8, v8
	v_mul_f32_e32 v9, 0xbfb8aa3b, v7
	v_exp_f32_e32 v9, v9
	v_mul_f32_e32 v4, v5, v4
	v_add_f32_e32 v5, 1.0, v8
	v_rcp_f32_e32 v5, v5
	v_add_f32_e32 v8, 1.0, v9
	v_rcp_f32_e32 v8, v8
	v_mul_f32_e32 v1, v1, v4
	v_mul_f32_e32 v4, v6, v5
	v_mul_f32_e32 v2, v2, v4
	v_mul_f32_e32 v4, v7, v8
	s_andn2_b64 vcc, exec, s[8:9]
	s_mov_b64 s[8:9], -1
	v_mul_f32_e32 v3, v3, v4
	v_cvt_pk_bf16_f32 v0, v0, v1
	v_cvt_pk_bf16_f32 v1, v2, v3
	global_store_dwordx2 v[16:17], v[0:1], off offset:128
	s_cbranch_vccnz .LBB0_1430
	s_andn2_b64 vcc, exec, s[0:1]
	s_cbranch_vccnz .LBB0_1429
	s_barrier
	s_branch .LBB0_1429
